# scan token-1024 gate waits for a pool tile-arrival counter (bumped as soon as a pool rank's decay/a/k tiles are stored) instead of the whole pool pre-work barrier generation
# speedup vs baseline: 1.0190x; 1.0088x over previous
; __global__ void __launch_bounds__(256, 2) fwd_megakernel(Params p) {
;     ...
;         if (mine) {
;           for (int i = lo + start; i < hi; i += stride) gemm_tile<G_RWW>(p, b * 32 + (i >> 2), i & 3, 0, smem);
;           for (int i = lo + start; i < hi; i += stride) gemm_tile<G_RWA>(p, b * 32 + (i >> 2), i & 3, 0, smem);
;         }
;         if (stage == 0) {
;           for (int i = (X.rank + (X.cnt >> 1)) % X.cnt; i < 17; i += X.cnt) t0_item(p, b * 17 + i, smem);
.LBB0_365:
	s_cmp_eq_u32 s84, 0x80
	s_cbranch_scc0 .Lgate_sig_skip
	v_readlane_b32 s0, v254, 50
	v_readlane_b32 s1, v254, 51
	s_and_b64 vcc, exec, s[0:1]
	s_cbranch_vccz .Lgate_sig_skip
	s_waitcnt vmcnt(0)
	s_barrier
	v_cmp_eq_u32_e32 vcc, 0, v173
	s_and_saveexec_b64 s[0:1], vcc
	s_cbranch_execz .Lgate_sig_join
	v_mov_b32_e32 v0, 0
	v_mov_b32_e32 v2, 1
	global_atomic_add v0, v2, s[60:61] offset:16
.Lgate_sig_join:
	s_or_b64 exec, exec, s[0:1]
.Lgate_sig_skip:
	v_readlane_b32 s0, v254, 48
	v_readlane_b32 s1, v254, 49
	s_andn2_b64 vcc, exec, s[0:1]
	s_mov_b64 s[0:1], -1
	s_cbranch_vccnz .LBB0_386
	s_cmp_eq_u32 s77, 64
	s_cbranch_scc0 .Lt0_orig
	s_cmp_ge_i32 s85, 17
	s_cbranch_scc1 .LBB0_385
	s_branch .Lt0_go

; DI void scan_item(const Params& p, int b, int h, int half, char* smem, unsigned* pgen, unsigned kp) {
;     ...
;     __syncthreads();
;     convert(R);
;     if (c == 0 && ls == 0) override_t0();
;     *(float4*)(Rl + ls * 64 + lc) = pr;
;     *(float4*)(Wl + ls * 64 + lc) = pw;
;     *(float4*)(Kl + ls * 64 + lc) = pk;
;     *(float4*)(Vl + ls * 64 + lc) = pv;
;     *(float4*)(Al + ls * 64 + lc) = make_float4(-pkk.x, -pkk.y, -pkk.z, -pkk.w);
;     *(float4*)(Bl + ls * 64 + lc) = make_float4(pkk.x * pa.x, pkk.y * pa.y, pkk.z * pa.z, pkk.w * pa.w);
;     if ((tid & 15) == 0) BON[ls] = pbon;
;     __syncthreads();
;     if (c + 2 == (T / SC) / 4) {
;       if (tid == 0) {
;         while (__hip_atomic_load(pgen, __ATOMIC_RELAXED, __HIP_MEMORY_SCOPE_AGENT) < kp) __builtin_amdgcn_s_sleep(2);
;         __builtin_amdgcn_fence(__ATOMIC_ACQUIRE, "agent");
;         asm volatile("s_waitcnt vmcnt(0)" ::: "memory");
;       }
;       __syncthreads();
;     }
.LBB0_691:
	s_or_b64 exec, exec, s[4:5]
	s_waitcnt vmcnt(8)
	v_cvt_f32_f16_sdwa v43, v126 dst_sel:DWORD dst_unused:UNUSED_PAD src0_sel:WORD_1
	v_cvt_f32_f16_e32 v42, v126
	v_cvt_f32_f16_sdwa v45, v128 dst_sel:DWORD dst_unused:UNUSED_PAD src0_sel:WORD_1
	v_cvt_f32_f16_e32 v44, v128
	v_pk_add_f32 v[44:45], v[44:45], v[42:43] neg_lo:[0,1] neg_hi:[0,1]
	s_waitcnt lgkmcnt(0)
	v_pk_fma_f32 v[34:35], v[44:45], v[34:35], v[42:43]
	v_cvt_f32_f16_sdwa v43, v127 dst_sel:DWORD dst_unused:UNUSED_PAD src0_sel:WORD_1
	v_cvt_f32_f16_e32 v42, v127
	v_cvt_f32_f16_sdwa v45, v129 dst_sel:DWORD dst_unused:UNUSED_PAD src0_sel:WORD_1
	v_cvt_f32_f16_e32 v44, v129
	v_pk_add_f32 v[44:45], v[44:45], v[42:43] neg_lo:[0,1] neg_hi:[0,1]
	s_nop 0
	v_pk_fma_f32 v[36:37], v[44:45], v[36:37], v[42:43]
	ds_write_b128 v195, v[38:41]
	ds_write_b128 v195, v[2:5] offset:4096
	ds_write_b128 v195, v[46:49] offset:8192
	ds_write_b128 v195, v[34:37] offset:12288
	v_xor_b32_e32 v37, 0x80000000, v53
	v_xor_b32_e32 v36, 0x80000000, v52
	v_xor_b32_e32 v35, 0x80000000, v51
	v_xor_b32_e32 v34, 0x80000000, v50
	ds_write_b128 v195, v[34:37] offset:16384
	v_pk_mul_f32 v[36:37], v[52:53], v[56:57]
	v_pk_mul_f32 v[34:35], v[50:51], v[54:55]
	ds_write_b128 v195, v[34:37] offset:20480
	s_mov_b64 s[4:5], exec
	v_readlane_b32 s16, v252, 36
	v_readlane_b32 s17, v252, 37
	s_and_b64 s[16:17], s[4:5], s[16:17]
	s_mov_b64 exec, s[16:17]
	ds_write_b32 v171, v0 offset:28672
	s_or_b64 exec, exec, s[4:5]
	s_add_i32 s24, s25, 2
	s_cmp_lg_u32 s24, 64
	s_waitcnt lgkmcnt(0)
	s_barrier
	s_cbranch_scc1 .LBB0_699
	s_mov_b64 s[4:5], exec
	v_readlane_b32 s16, v252, 18
	v_readlane_b32 s17, v252, 19
	s_and_b64 s[16:17], s[4:5], s[16:17]
	s_mov_b64 exec, s[16:17]
	s_cbranch_execz .LBB0_698
	s_mul_i32 s97, s76, s77
	global_load_dword v0, v1, s[60:61] offset:16 sc1
	s_waitcnt vmcnt(0)
	v_cmp_le_u32_e32 vcc, s97, v0
	s_cbranch_vccnz .LBB0_697
.LBB0_696:
	s_sleep 2
	global_load_dword v0, v1, s[60:61] offset:16 sc1
	s_waitcnt vmcnt(0)
	v_cmp_gt_u32_e32 vcc, s97, v0
	s_cbranch_vccnz .LBB0_696
